# retention-projection GEMM epilogue: 32 dwordx2 stores -> 16 dwordx4 via v_permlane16_swap row-block pairing (hand-written block)
# baseline (speedup 1.0000x reference)
.LBB0_147:
	v_or_b32_e32 v130, s48, v158
	v_add_u32_e32 v134, v130, v159
	v_lshlrev_b32_e32 v130, 5, v156
	v_lshlrev_b32_e32 v131, 2, v157
	v_or3_b32 v130, v130, v131, s46
	v_ashrrev_i32_e32 v131, 31, v130
	v_lshlrev_b64 v[130:131], 1, v[130:131]
	v_bfe_u32 v208, v154, 4, 1
	v_mul_u32_u24_e32 v208, 0x19ff8, v208
	v_mov_b32_e32 v209, 0
	v_lshl_add_u64 v[130:131], v[130:131], 0, v[208:209]
	v_mov_b64_e32 v[210:211], s[12:13]
	v_mad_i64_i32 v[214:215], s[4:5], v134, s61, v[210:211]
	v_lshl_add_u64 v[214:215], v[214:215], 0, v[130:131]
	v_cvt_pk_bf16_f32 v176, v124, v125
	v_cvt_pk_bf16_f32 v177, v126, v127
	v_cvt_pk_bf16_f32 v178, v116, v117
	v_cvt_pk_bf16_f32 v179, v118, v119
	s_nop 1
	v_permlane16_swap_b32_e32 v176, v178
	v_permlane16_swap_b32_e32 v177, v179
	global_store_dwordx4 v[214:215], v[176:179], off
	v_cvt_pk_bf16_f32 v180, v120, v121
	v_cvt_pk_bf16_f32 v181, v122, v123
	v_cvt_pk_bf16_f32 v182, v112, v113
	v_cvt_pk_bf16_f32 v183, v114, v115
	s_nop 1
	v_permlane16_swap_b32_e32 v180, v182
	v_permlane16_swap_b32_e32 v181, v183
	global_store_dwordx4 v[214:215], v[180:183], off offset:32
	v_cvt_pk_bf16_f32 v184, v100, v101
	v_cvt_pk_bf16_f32 v185, v102, v103
	v_cvt_pk_bf16_f32 v186, v88, v89
	v_cvt_pk_bf16_f32 v187, v90, v91
	s_nop 1
	v_permlane16_swap_b32_e32 v184, v186
	v_permlane16_swap_b32_e32 v185, v187
	global_store_dwordx4 v[214:215], v[184:187], off offset:256
	v_cvt_pk_bf16_f32 v188, v92, v93
	v_cvt_pk_bf16_f32 v189, v94, v95
	v_cvt_pk_bf16_f32 v190, v80, v81
	v_cvt_pk_bf16_f32 v191, v82, v83
	s_nop 1
	v_permlane16_swap_b32_e32 v188, v190
	v_permlane16_swap_b32_e32 v189, v191
	global_store_dwordx4 v[214:215], v[188:191], off offset:288
	v_add_u32_e32 v212, 0x20, v134
	v_mad_i64_i32 v[216:217], s[4:5], v212, s61, v[210:211]
	v_lshl_add_u64 v[216:217], v[216:217], 0, v[130:131]
	v_cvt_pk_bf16_f32 v192, v108, v109
	v_cvt_pk_bf16_f32 v193, v110, v111
	v_cvt_pk_bf16_f32 v194, v96, v97
	v_cvt_pk_bf16_f32 v195, v98, v99
	s_nop 1
	v_permlane16_swap_b32_e32 v192, v194
	v_permlane16_swap_b32_e32 v193, v195
	global_store_dwordx4 v[216:217], v[192:195], off
	v_cvt_pk_bf16_f32 v196, v104, v105
	v_cvt_pk_bf16_f32 v197, v106, v107
	v_cvt_pk_bf16_f32 v198, v84, v85
	v_cvt_pk_bf16_f32 v199, v86, v87
	s_nop 1
	v_permlane16_swap_b32_e32 v196, v198
	v_permlane16_swap_b32_e32 v197, v199
	global_store_dwordx4 v[216:217], v[196:199], off offset:32
	v_cvt_pk_bf16_f32 v200, v72, v73
	v_cvt_pk_bf16_f32 v201, v74, v75
	v_cvt_pk_bf16_f32 v202, v60, v61
	v_cvt_pk_bf16_f32 v203, v62, v63
	s_nop 1
	v_permlane16_swap_b32_e32 v200, v202
	v_permlane16_swap_b32_e32 v201, v203
	global_store_dwordx4 v[216:217], v[200:203], off offset:256
	v_cvt_pk_bf16_f32 v204, v68, v69
	v_cvt_pk_bf16_f32 v205, v70, v71
	v_cvt_pk_bf16_f32 v206, v52, v53
	v_cvt_pk_bf16_f32 v207, v54, v55
	s_nop 1
	v_permlane16_swap_b32_e32 v204, v206
	v_permlane16_swap_b32_e32 v205, v207
	global_store_dwordx4 v[216:217], v[204:207], off offset:288
	v_add_u32_e32 v212, 0x80, v134
	v_mad_i64_i32 v[218:219], s[4:5], v212, s61, v[210:211]
	v_lshl_add_u64 v[218:219], v[218:219], 0, v[130:131]
	v_cvt_pk_bf16_f32 v176, v76, v77
	v_cvt_pk_bf16_f32 v177, v78, v79
	v_cvt_pk_bf16_f32 v178, v56, v57
	v_cvt_pk_bf16_f32 v179, v58, v59
	s_nop 1
	v_permlane16_swap_b32_e32 v176, v178
	v_permlane16_swap_b32_e32 v177, v179
	global_store_dwordx4 v[218:219], v[176:179], off
	v_cvt_pk_bf16_f32 v180, v64, v65
	v_cvt_pk_bf16_f32 v181, v66, v67
	v_cvt_pk_bf16_f32 v182, v48, v49
	v_cvt_pk_bf16_f32 v183, v50, v51
	s_nop 1
	v_permlane16_swap_b32_e32 v180, v182
	v_permlane16_swap_b32_e32 v181, v183
	global_store_dwordx4 v[218:219], v[180:183], off offset:32
	v_cvt_pk_bf16_f32 v184, v28, v29
	v_cvt_pk_bf16_f32 v185, v30, v31
	v_cvt_pk_bf16_f32 v186, v20, v21
	v_cvt_pk_bf16_f32 v187, v22, v23
	s_nop 1
	v_permlane16_swap_b32_e32 v184, v186
	v_permlane16_swap_b32_e32 v185, v187
	global_store_dwordx4 v[218:219], v[184:187], off offset:256
	v_cvt_pk_bf16_f32 v188, v24, v25
	v_cvt_pk_bf16_f32 v189, v26, v27
	v_cvt_pk_bf16_f32 v190, v16, v17
	v_cvt_pk_bf16_f32 v191, v18, v19
	s_nop 1
	v_permlane16_swap_b32_e32 v188, v190
	v_permlane16_swap_b32_e32 v189, v191
	global_store_dwordx4 v[218:219], v[188:191], off offset:288
	v_add_u32_e32 v212, 0xa0, v134
	v_mad_i64_i32 v[220:221], s[4:5], v212, s61, v[210:211]
	v_lshl_add_u64 v[220:221], v[220:221], 0, v[130:131]
	v_cvt_pk_bf16_f32 v192, v44, v45
	v_cvt_pk_bf16_f32 v193, v46, v47
	v_cvt_pk_bf16_f32 v194, v36, v37
	v_cvt_pk_bf16_f32 v195, v38, v39
	s_nop 1
	v_permlane16_swap_b32_e32 v192, v194
	v_permlane16_swap_b32_e32 v193, v195
	global_store_dwordx4 v[220:221], v[192:195], off
	v_cvt_pk_bf16_f32 v196, v40, v41
	v_cvt_pk_bf16_f32 v197, v42, v43
	v_cvt_pk_bf16_f32 v198, v32, v33
	v_cvt_pk_bf16_f32 v199, v34, v35
	s_nop 1
	v_permlane16_swap_b32_e32 v196, v198
	v_permlane16_swap_b32_e32 v197, v199
	global_store_dwordx4 v[220:221], v[196:199], off offset:32
	v_cvt_pk_bf16_f32 v200, v12, v13
	v_cvt_pk_bf16_f32 v201, v14, v15
	v_cvt_pk_bf16_f32 v202, v4, v5
	v_cvt_pk_bf16_f32 v203, v6, v7
	s_nop 1
	v_permlane16_swap_b32_e32 v200, v202
	v_permlane16_swap_b32_e32 v201, v203
	global_store_dwordx4 v[220:221], v[200:203], off offset:256
	v_cvt_pk_bf16_f32 v204, v8, v9
	v_cvt_pk_bf16_f32 v205, v10, v11
	v_cvt_pk_bf16_f32 v206, v0, v1
	v_cvt_pk_bf16_f32 v207, v2, v3
	s_nop 1
	v_permlane16_swap_b32_e32 v204, v206
	v_permlane16_swap_b32_e32 v205, v207
	global_store_dwordx4 v[220:221], v[204:207], off offset:288
	s_mov_b64 s[4:5], -1
	s_andn2_b64 vcc, exec, s[0:1]
	s_mov_b32 s14, s63
	s_mov_b32 s65, s64
	s_cbranch_vccz .LBB0_164
